# P1 gate-tile epilogue: sigmoid in place on accumulators with packed ops and folded power-of-two scale (fewer VALU per step)
# speedup vs baseline: 1.0105x; 1.0015x over previous
.LBB0_155:
	v_lshl_add_u32 v24, s42, 8, v200
	v_lshlrev_b32_e32 v24, 1, v24
	v_lshl_add_u32 v12, v2, 13, v24
	v_add_u32_e32 v13, 0x20000, v12
	v_add_u32_e32 v14, 0x40000, v12
	v_add_u32_e32 v15, 0x60000, v12
	v_add_u32_e32 v16, 0x100000, v12
	v_add_u32_e32 v17, 0x120000, v12
	v_add_u32_e32 v18, 0x140000, v12
	v_add_u32_e32 v19, 0x160000, v12
	v_mov_b32_e32 v22, 1.0
	v_mov_b32_e32 v23, 1.0
	v_mov_b32_e32 v20, 0xbfb8aa3b
	v_mul_f32_e32 v20, s24, v20
	v_mov_b32_e32 v21, v20
	v_pk_mul_f32 v[158:159], v[158:159], v[20:21]
	v_pk_mul_f32 v[160:161], v[160:161], v[20:21]
	v_pk_mul_f32 v[154:155], v[154:155], v[20:21]
	v_pk_mul_f32 v[156:157], v[156:157], v[20:21]
	v_exp_f32_e32 v158, v158
	v_exp_f32_e32 v159, v159
	v_exp_f32_e32 v160, v160
	v_exp_f32_e32 v161, v161
	v_exp_f32_e32 v154, v154
	v_exp_f32_e32 v155, v155
	v_exp_f32_e32 v156, v156
	v_exp_f32_e32 v157, v157
	v_pk_add_f32 v[158:159], v[158:159], v[22:23]
	v_pk_add_f32 v[160:161], v[160:161], v[22:23]
	v_pk_add_f32 v[154:155], v[154:155], v[22:23]
	v_pk_add_f32 v[156:157], v[156:157], v[22:23]
	v_rcp_f32_e32 v158, v158
	v_rcp_f32_e32 v159, v159
	v_rcp_f32_e32 v160, v160
	v_rcp_f32_e32 v161, v161
	v_rcp_f32_e32 v154, v154
	v_rcp_f32_e32 v155, v155
	v_rcp_f32_e32 v156, v156
	v_rcp_f32_e32 v157, v157
	v_cvt_pk_bf16_f32 v8, v158, v159
	v_cvt_pk_bf16_f32 v9, v160, v161
	v_cvt_pk_bf16_f32 v10, v154, v155
	v_cvt_pk_bf16_f32 v11, v156, v157
	global_store_dwordx4 v12, v[8:11], s[20:21] offset:0
	v_pk_mul_f32 v[150:151], v[150:151], v[20:21]
	v_pk_mul_f32 v[152:153], v[152:153], v[20:21]
	v_pk_mul_f32 v[146:147], v[146:147], v[20:21]
	v_pk_mul_f32 v[148:149], v[148:149], v[20:21]
	v_exp_f32_e32 v150, v150
	v_exp_f32_e32 v151, v151
	v_exp_f32_e32 v152, v152
	v_exp_f32_e32 v153, v153
	v_exp_f32_e32 v146, v146
	v_exp_f32_e32 v147, v147
	v_exp_f32_e32 v148, v148
	v_exp_f32_e32 v149, v149
	v_pk_add_f32 v[150:151], v[150:151], v[22:23]
	v_pk_add_f32 v[152:153], v[152:153], v[22:23]
	v_pk_add_f32 v[146:147], v[146:147], v[22:23]
	v_pk_add_f32 v[148:149], v[148:149], v[22:23]
	v_rcp_f32_e32 v150, v150
	v_rcp_f32_e32 v151, v151
	v_rcp_f32_e32 v152, v152
	v_rcp_f32_e32 v153, v153
	v_rcp_f32_e32 v146, v146
	v_rcp_f32_e32 v147, v147
	v_rcp_f32_e32 v148, v148
	v_rcp_f32_e32 v149, v149
	s_nop 0
	v_cvt_pk_bf16_f32 v8, v150, v151
	v_cvt_pk_bf16_f32 v9, v152, v153
	v_cvt_pk_bf16_f32 v10, v146, v147
	v_cvt_pk_bf16_f32 v11, v148, v149
	global_store_dwordx4 v12, v[8:11], s[20:21] offset:256
	v_pk_mul_f32 v[142:143], v[142:143], v[20:21]
	v_pk_mul_f32 v[144:145], v[144:145], v[20:21]
	v_pk_mul_f32 v[138:139], v[138:139], v[20:21]
	v_pk_mul_f32 v[140:141], v[140:141], v[20:21]
	v_exp_f32_e32 v142, v142
	v_exp_f32_e32 v143, v143
	v_exp_f32_e32 v144, v144
	v_exp_f32_e32 v145, v145
	v_exp_f32_e32 v138, v138
	v_exp_f32_e32 v139, v139
	v_exp_f32_e32 v140, v140
	v_exp_f32_e32 v141, v141
	v_pk_add_f32 v[142:143], v[142:143], v[22:23]
	v_pk_add_f32 v[144:145], v[144:145], v[22:23]
	v_pk_add_f32 v[138:139], v[138:139], v[22:23]
	v_pk_add_f32 v[140:141], v[140:141], v[22:23]
	v_rcp_f32_e32 v142, v142
	v_rcp_f32_e32 v143, v143
	v_rcp_f32_e32 v144, v144
	v_rcp_f32_e32 v145, v145
	v_rcp_f32_e32 v138, v138
	v_rcp_f32_e32 v139, v139
	v_rcp_f32_e32 v140, v140
	v_rcp_f32_e32 v141, v141
	s_nop 0
	v_cvt_pk_bf16_f32 v8, v142, v143
	v_cvt_pk_bf16_f32 v9, v144, v145
	v_cvt_pk_bf16_f32 v10, v138, v139
	v_cvt_pk_bf16_f32 v11, v140, v141
	global_store_dwordx4 v13, v[8:11], s[20:21] offset:0
	v_pk_mul_f32 v[134:135], v[134:135], v[20:21]
	v_pk_mul_f32 v[136:137], v[136:137], v[20:21]
	v_pk_mul_f32 v[130:131], v[130:131], v[20:21]
	v_pk_mul_f32 v[132:133], v[132:133], v[20:21]
	v_exp_f32_e32 v134, v134
	v_exp_f32_e32 v135, v135
	v_exp_f32_e32 v136, v136
	v_exp_f32_e32 v137, v137
	v_exp_f32_e32 v130, v130
	v_exp_f32_e32 v131, v131
	v_exp_f32_e32 v132, v132
	v_exp_f32_e32 v133, v133
	v_pk_add_f32 v[134:135], v[134:135], v[22:23]
	v_pk_add_f32 v[136:137], v[136:137], v[22:23]
	v_pk_add_f32 v[130:131], v[130:131], v[22:23]
	v_pk_add_f32 v[132:133], v[132:133], v[22:23]
	v_rcp_f32_e32 v134, v134
	v_rcp_f32_e32 v135, v135
	v_rcp_f32_e32 v136, v136
	v_rcp_f32_e32 v137, v137
	v_rcp_f32_e32 v130, v130
	v_rcp_f32_e32 v131, v131
	v_rcp_f32_e32 v132, v132
	v_rcp_f32_e32 v133, v133
	s_nop 0
	v_cvt_pk_bf16_f32 v8, v134, v135
	v_cvt_pk_bf16_f32 v9, v136, v137
	v_cvt_pk_bf16_f32 v10, v130, v131
	v_cvt_pk_bf16_f32 v11, v132, v133
	global_store_dwordx4 v13, v[8:11], s[20:21] offset:256
	v_pk_mul_f32 v[126:127], v[126:127], v[20:21]
	v_pk_mul_f32 v[128:129], v[128:129], v[20:21]
	v_pk_mul_f32 v[122:123], v[122:123], v[20:21]
	v_pk_mul_f32 v[124:125], v[124:125], v[20:21]
	v_exp_f32_e32 v126, v126
	v_exp_f32_e32 v127, v127
	v_exp_f32_e32 v128, v128
	v_exp_f32_e32 v129, v129
	v_exp_f32_e32 v122, v122
	v_exp_f32_e32 v123, v123
	v_exp_f32_e32 v124, v124
	v_exp_f32_e32 v125, v125
	v_pk_add_f32 v[126:127], v[126:127], v[22:23]
	v_pk_add_f32 v[128:129], v[128:129], v[22:23]
	v_pk_add_f32 v[122:123], v[122:123], v[22:23]
	v_pk_add_f32 v[124:125], v[124:125], v[22:23]
	v_rcp_f32_e32 v126, v126
	v_rcp_f32_e32 v127, v127
	v_rcp_f32_e32 v128, v128
	v_rcp_f32_e32 v129, v129
	v_rcp_f32_e32 v122, v122
	v_rcp_f32_e32 v123, v123
	v_rcp_f32_e32 v124, v124
	v_rcp_f32_e32 v125, v125
	s_nop 0
	v_cvt_pk_bf16_f32 v8, v126, v127
	v_cvt_pk_bf16_f32 v9, v128, v129
	v_cvt_pk_bf16_f32 v10, v122, v123
	v_cvt_pk_bf16_f32 v11, v124, v125
	global_store_dwordx4 v14, v[8:11], s[20:21] offset:0
	v_pk_mul_f32 v[118:119], v[118:119], v[20:21]
	v_pk_mul_f32 v[120:121], v[120:121], v[20:21]
	v_pk_mul_f32 v[114:115], v[114:115], v[20:21]
	v_pk_mul_f32 v[116:117], v[116:117], v[20:21]
	v_exp_f32_e32 v118, v118
	v_exp_f32_e32 v119, v119
	v_exp_f32_e32 v120, v120
	v_exp_f32_e32 v121, v121
	v_exp_f32_e32 v114, v114
	v_exp_f32_e32 v115, v115
	v_exp_f32_e32 v116, v116
	v_exp_f32_e32 v117, v117
	v_pk_add_f32 v[118:119], v[118:119], v[22:23]
	v_pk_add_f32 v[120:121], v[120:121], v[22:23]
	v_pk_add_f32 v[114:115], v[114:115], v[22:23]
	v_pk_add_f32 v[116:117], v[116:117], v[22:23]
	v_rcp_f32_e32 v118, v118
	v_rcp_f32_e32 v119, v119
	v_rcp_f32_e32 v120, v120
	v_rcp_f32_e32 v121, v121
	v_rcp_f32_e32 v114, v114
	v_rcp_f32_e32 v115, v115
	v_rcp_f32_e32 v116, v116
	v_rcp_f32_e32 v117, v117
	s_nop 0
	v_cvt_pk_bf16_f32 v8, v118, v119
	v_cvt_pk_bf16_f32 v9, v120, v121
	v_cvt_pk_bf16_f32 v10, v114, v115
	v_cvt_pk_bf16_f32 v11, v116, v117
	global_store_dwordx4 v14, v[8:11], s[20:21] offset:256
	v_pk_mul_f32 v[110:111], v[110:111], v[20:21]
	v_pk_mul_f32 v[112:113], v[112:113], v[20:21]
	v_pk_mul_f32 v[106:107], v[106:107], v[20:21]
	v_pk_mul_f32 v[108:109], v[108:109], v[20:21]
	v_exp_f32_e32 v110, v110
	v_exp_f32_e32 v111, v111
	v_exp_f32_e32 v112, v112
	v_exp_f32_e32 v113, v113
	v_exp_f32_e32 v106, v106
	v_exp_f32_e32 v107, v107
	v_exp_f32_e32 v108, v108
	v_exp_f32_e32 v109, v109
	v_pk_add_f32 v[110:111], v[110:111], v[22:23]
	v_pk_add_f32 v[112:113], v[112:113], v[22:23]
	v_pk_add_f32 v[106:107], v[106:107], v[22:23]
	v_pk_add_f32 v[108:109], v[108:109], v[22:23]
	v_rcp_f32_e32 v110, v110
	v_rcp_f32_e32 v111, v111
	v_rcp_f32_e32 v112, v112
	v_rcp_f32_e32 v113, v113
	v_rcp_f32_e32 v106, v106
	v_rcp_f32_e32 v107, v107
	v_rcp_f32_e32 v108, v108
	v_rcp_f32_e32 v109, v109
	s_nop 0
	v_cvt_pk_bf16_f32 v8, v110, v111
	v_cvt_pk_bf16_f32 v9, v112, v113
	v_cvt_pk_bf16_f32 v10, v106, v107
	v_cvt_pk_bf16_f32 v11, v108, v109
	global_store_dwordx4 v15, v[8:11], s[20:21] offset:0
	v_pk_mul_f32 v[102:103], v[102:103], v[20:21]
	v_pk_mul_f32 v[104:105], v[104:105], v[20:21]
	v_pk_mul_f32 v[98:99], v[98:99], v[20:21]
	v_pk_mul_f32 v[100:101], v[100:101], v[20:21]
	v_exp_f32_e32 v102, v102
	v_exp_f32_e32 v103, v103
	v_exp_f32_e32 v104, v104
	v_exp_f32_e32 v105, v105
	v_exp_f32_e32 v98, v98
	v_exp_f32_e32 v99, v99
	v_exp_f32_e32 v100, v100
	v_exp_f32_e32 v101, v101
	v_pk_add_f32 v[102:103], v[102:103], v[22:23]
	v_pk_add_f32 v[104:105], v[104:105], v[22:23]
	v_pk_add_f32 v[98:99], v[98:99], v[22:23]
	v_pk_add_f32 v[100:101], v[100:101], v[22:23]
	v_rcp_f32_e32 v102, v102
	v_rcp_f32_e32 v103, v103
	v_rcp_f32_e32 v104, v104
	v_rcp_f32_e32 v105, v105
	v_rcp_f32_e32 v98, v98
	v_rcp_f32_e32 v99, v99
	v_rcp_f32_e32 v100, v100
	v_rcp_f32_e32 v101, v101
	s_nop 0
	v_cvt_pk_bf16_f32 v8, v102, v103
	v_cvt_pk_bf16_f32 v9, v104, v105
	v_cvt_pk_bf16_f32 v10, v98, v99
	v_cvt_pk_bf16_f32 v11, v100, v101
	global_store_dwordx4 v15, v[8:11], s[20:21] offset:256
	v_pk_mul_f32 v[94:95], v[94:95], v[20:21]
	v_pk_mul_f32 v[96:97], v[96:97], v[20:21]
	v_pk_mul_f32 v[90:91], v[90:91], v[20:21]
	v_pk_mul_f32 v[92:93], v[92:93], v[20:21]
	v_exp_f32_e32 v94, v94
	v_exp_f32_e32 v95, v95
	v_exp_f32_e32 v96, v96
	v_exp_f32_e32 v97, v97
	v_exp_f32_e32 v90, v90
	v_exp_f32_e32 v91, v91
	v_exp_f32_e32 v92, v92
	v_exp_f32_e32 v93, v93
	v_pk_add_f32 v[94:95], v[94:95], v[22:23]
	v_pk_add_f32 v[96:97], v[96:97], v[22:23]
	v_pk_add_f32 v[90:91], v[90:91], v[22:23]
	v_pk_add_f32 v[92:93], v[92:93], v[22:23]
	v_rcp_f32_e32 v94, v94
	v_rcp_f32_e32 v95, v95
	v_rcp_f32_e32 v96, v96
	v_rcp_f32_e32 v97, v97
	v_rcp_f32_e32 v90, v90
	v_rcp_f32_e32 v91, v91
	v_rcp_f32_e32 v92, v92
	v_rcp_f32_e32 v93, v93
	s_nop 0
	v_cvt_pk_bf16_f32 v8, v94, v95
	v_cvt_pk_bf16_f32 v9, v96, v97
	v_cvt_pk_bf16_f32 v10, v90, v91
	v_cvt_pk_bf16_f32 v11, v92, v93
	global_store_dwordx4 v16, v[8:11], s[20:21] offset:0
	v_pk_mul_f32 v[86:87], v[86:87], v[20:21]
	v_pk_mul_f32 v[88:89], v[88:89], v[20:21]
	v_pk_mul_f32 v[82:83], v[82:83], v[20:21]
	v_pk_mul_f32 v[84:85], v[84:85], v[20:21]
	v_exp_f32_e32 v86, v86
	v_exp_f32_e32 v87, v87
	v_exp_f32_e32 v88, v88
	v_exp_f32_e32 v89, v89
	v_exp_f32_e32 v82, v82
	v_exp_f32_e32 v83, v83
	v_exp_f32_e32 v84, v84
	v_exp_f32_e32 v85, v85
	v_pk_add_f32 v[86:87], v[86:87], v[22:23]
	v_pk_add_f32 v[88:89], v[88:89], v[22:23]
	v_pk_add_f32 v[82:83], v[82:83], v[22:23]
	v_pk_add_f32 v[84:85], v[84:85], v[22:23]
	v_rcp_f32_e32 v86, v86
	v_rcp_f32_e32 v87, v87
	v_rcp_f32_e32 v88, v88
	v_rcp_f32_e32 v89, v89
	v_rcp_f32_e32 v82, v82
	v_rcp_f32_e32 v83, v83
	v_rcp_f32_e32 v84, v84
	v_rcp_f32_e32 v85, v85
	s_nop 0
	v_cvt_pk_bf16_f32 v8, v86, v87
	v_cvt_pk_bf16_f32 v9, v88, v89
	v_cvt_pk_bf16_f32 v10, v82, v83
	v_cvt_pk_bf16_f32 v11, v84, v85
	global_store_dwordx4 v16, v[8:11], s[20:21] offset:256
	v_pk_mul_f32 v[78:79], v[78:79], v[20:21]
	v_pk_mul_f32 v[80:81], v[80:81], v[20:21]
	v_pk_mul_f32 v[74:75], v[74:75], v[20:21]
	v_pk_mul_f32 v[76:77], v[76:77], v[20:21]
	v_exp_f32_e32 v78, v78
	v_exp_f32_e32 v79, v79
	v_exp_f32_e32 v80, v80
	v_exp_f32_e32 v81, v81
	v_exp_f32_e32 v74, v74
	v_exp_f32_e32 v75, v75
	v_exp_f32_e32 v76, v76
	v_exp_f32_e32 v77, v77
	v_pk_add_f32 v[78:79], v[78:79], v[22:23]
	v_pk_add_f32 v[80:81], v[80:81], v[22:23]
	v_pk_add_f32 v[74:75], v[74:75], v[22:23]
	v_pk_add_f32 v[76:77], v[76:77], v[22:23]
	v_rcp_f32_e32 v78, v78
	v_rcp_f32_e32 v79, v79
	v_rcp_f32_e32 v80, v80
	v_rcp_f32_e32 v81, v81
	v_rcp_f32_e32 v74, v74
	v_rcp_f32_e32 v75, v75
	v_rcp_f32_e32 v76, v76
	v_rcp_f32_e32 v77, v77
	s_nop 0
	v_cvt_pk_bf16_f32 v8, v78, v79
	v_cvt_pk_bf16_f32 v9, v80, v81
	v_cvt_pk_bf16_f32 v10, v74, v75
	v_cvt_pk_bf16_f32 v11, v76, v77
	global_store_dwordx4 v17, v[8:11], s[20:21] offset:0
	v_pk_mul_f32 v[70:71], v[70:71], v[20:21]
	v_pk_mul_f32 v[72:73], v[72:73], v[20:21]
	v_pk_mul_f32 v[66:67], v[66:67], v[20:21]
	v_pk_mul_f32 v[68:69], v[68:69], v[20:21]
	v_exp_f32_e32 v70, v70
	v_exp_f32_e32 v71, v71
	v_exp_f32_e32 v72, v72
	v_exp_f32_e32 v73, v73
	v_exp_f32_e32 v66, v66
	v_exp_f32_e32 v67, v67
	v_exp_f32_e32 v68, v68
	v_exp_f32_e32 v69, v69
	v_pk_add_f32 v[70:71], v[70:71], v[22:23]
	v_pk_add_f32 v[72:73], v[72:73], v[22:23]
	v_pk_add_f32 v[66:67], v[66:67], v[22:23]
	v_pk_add_f32 v[68:69], v[68:69], v[22:23]
	v_rcp_f32_e32 v70, v70
	v_rcp_f32_e32 v71, v71
	v_rcp_f32_e32 v72, v72
	v_rcp_f32_e32 v73, v73
	v_rcp_f32_e32 v66, v66
	v_rcp_f32_e32 v67, v67
	v_rcp_f32_e32 v68, v68
	v_rcp_f32_e32 v69, v69
	s_nop 0
	v_cvt_pk_bf16_f32 v8, v70, v71
	v_cvt_pk_bf16_f32 v9, v72, v73
	v_cvt_pk_bf16_f32 v10, v66, v67
	v_cvt_pk_bf16_f32 v11, v68, v69
	global_store_dwordx4 v17, v[8:11], s[20:21] offset:256
	v_pk_mul_f32 v[62:63], v[62:63], v[20:21]
	v_pk_mul_f32 v[64:65], v[64:65], v[20:21]
	v_pk_mul_f32 v[58:59], v[58:59], v[20:21]
	v_pk_mul_f32 v[60:61], v[60:61], v[20:21]
	v_exp_f32_e32 v62, v62
	v_exp_f32_e32 v63, v63
	v_exp_f32_e32 v64, v64
	v_exp_f32_e32 v65, v65
	v_exp_f32_e32 v58, v58
	v_exp_f32_e32 v59, v59
	v_exp_f32_e32 v60, v60
	v_exp_f32_e32 v61, v61
	v_pk_add_f32 v[62:63], v[62:63], v[22:23]
	v_pk_add_f32 v[64:65], v[64:65], v[22:23]
	v_pk_add_f32 v[58:59], v[58:59], v[22:23]
	v_pk_add_f32 v[60:61], v[60:61], v[22:23]
	v_rcp_f32_e32 v62, v62
	v_rcp_f32_e32 v63, v63
	v_rcp_f32_e32 v64, v64
	v_rcp_f32_e32 v65, v65
	v_rcp_f32_e32 v58, v58
	v_rcp_f32_e32 v59, v59
	v_rcp_f32_e32 v60, v60
	v_rcp_f32_e32 v61, v61
	s_nop 0
	v_cvt_pk_bf16_f32 v8, v62, v63
	v_cvt_pk_bf16_f32 v9, v64, v65
	v_cvt_pk_bf16_f32 v10, v58, v59
	v_cvt_pk_bf16_f32 v11, v60, v61
	global_store_dwordx4 v18, v[8:11], s[20:21] offset:0
	v_pk_mul_f32 v[54:55], v[54:55], v[20:21]
	v_pk_mul_f32 v[56:57], v[56:57], v[20:21]
	v_pk_mul_f32 v[50:51], v[50:51], v[20:21]
	v_pk_mul_f32 v[52:53], v[52:53], v[20:21]
	v_exp_f32_e32 v54, v54
	v_exp_f32_e32 v55, v55
	v_exp_f32_e32 v56, v56
	v_exp_f32_e32 v57, v57
	v_exp_f32_e32 v50, v50
	v_exp_f32_e32 v51, v51
	v_exp_f32_e32 v52, v52
	v_exp_f32_e32 v53, v53
	v_pk_add_f32 v[54:55], v[54:55], v[22:23]
	v_pk_add_f32 v[56:57], v[56:57], v[22:23]
	v_pk_add_f32 v[50:51], v[50:51], v[22:23]
	v_pk_add_f32 v[52:53], v[52:53], v[22:23]
	v_rcp_f32_e32 v54, v54
	v_rcp_f32_e32 v55, v55
	v_rcp_f32_e32 v56, v56
	v_rcp_f32_e32 v57, v57
	v_rcp_f32_e32 v50, v50
	v_rcp_f32_e32 v51, v51
	v_rcp_f32_e32 v52, v52
	v_rcp_f32_e32 v53, v53
	s_nop 0
	v_cvt_pk_bf16_f32 v8, v54, v55
	v_cvt_pk_bf16_f32 v9, v56, v57
	v_cvt_pk_bf16_f32 v10, v50, v51
	v_cvt_pk_bf16_f32 v11, v52, v53
	global_store_dwordx4 v18, v[8:11], s[20:21] offset:256
	v_pk_mul_f32 v[46:47], v[46:47], v[20:21]
	v_pk_mul_f32 v[48:49], v[48:49], v[20:21]
	v_pk_mul_f32 v[42:43], v[42:43], v[20:21]
	v_pk_mul_f32 v[44:45], v[44:45], v[20:21]
	v_exp_f32_e32 v46, v46
	v_exp_f32_e32 v47, v47
	v_exp_f32_e32 v48, v48
	v_exp_f32_e32 v49, v49
	v_exp_f32_e32 v42, v42
	v_exp_f32_e32 v43, v43
	v_exp_f32_e32 v44, v44
	v_exp_f32_e32 v45, v45
	v_pk_add_f32 v[46:47], v[46:47], v[22:23]
	v_pk_add_f32 v[48:49], v[48:49], v[22:23]
	v_pk_add_f32 v[42:43], v[42:43], v[22:23]
	v_pk_add_f32 v[44:45], v[44:45], v[22:23]
	v_rcp_f32_e32 v46, v46
	v_rcp_f32_e32 v47, v47
	v_rcp_f32_e32 v48, v48
	v_rcp_f32_e32 v49, v49
	v_rcp_f32_e32 v42, v42
	v_rcp_f32_e32 v43, v43
	v_rcp_f32_e32 v44, v44
	v_rcp_f32_e32 v45, v45
	s_nop 0
	v_cvt_pk_bf16_f32 v8, v46, v47
	v_cvt_pk_bf16_f32 v9, v48, v49
	v_cvt_pk_bf16_f32 v10, v42, v43
	v_cvt_pk_bf16_f32 v11, v44, v45
	global_store_dwordx4 v19, v[8:11], s[20:21] offset:0
	v_pk_mul_f32 v[38:39], v[38:39], v[20:21]
	v_pk_mul_f32 v[40:41], v[40:41], v[20:21]
	v_pk_mul_f32 v[34:35], v[34:35], v[20:21]
	v_pk_mul_f32 v[36:37], v[36:37], v[20:21]
	v_exp_f32_e32 v38, v38
	v_exp_f32_e32 v39, v39
	v_exp_f32_e32 v40, v40
	v_exp_f32_e32 v41, v41
	v_exp_f32_e32 v34, v34
	v_exp_f32_e32 v35, v35
	v_exp_f32_e32 v36, v36
	v_exp_f32_e32 v37, v37
	v_pk_add_f32 v[38:39], v[38:39], v[22:23]
	v_pk_add_f32 v[40:41], v[40:41], v[22:23]
	v_pk_add_f32 v[34:35], v[34:35], v[22:23]
	v_pk_add_f32 v[36:37], v[36:37], v[22:23]
	v_rcp_f32_e32 v38, v38
	v_rcp_f32_e32 v39, v39
	v_rcp_f32_e32 v40, v40
	v_rcp_f32_e32 v41, v41
	v_rcp_f32_e32 v34, v34
	v_rcp_f32_e32 v35, v35
	v_rcp_f32_e32 v36, v36
	v_rcp_f32_e32 v37, v37
	s_nop 0
	v_cvt_pk_bf16_f32 v8, v38, v39
	v_cvt_pk_bf16_f32 v9, v40, v41
	v_cvt_pk_bf16_f32 v10, v34, v35
	v_cvt_pk_bf16_f32 v11, v36, v37
	global_store_dwordx4 v19, v[8:11], s[20:21] offset:256
	s_andn2_b64 vcc, exec, s[0:1]
	s_mov_b64 s[0:1], -1
	s_cbranch_vccnz .LBB0_126
